# v73 + prologue DMA(0)/DMA(1) issued together (counted vmcnt(4)) + younger-half score block at s_setprio 2
# baseline (speedup 1.0000x reference)
; #define SBAR() __builtin_amdgcn_sched_barrier(0)
; __device__ __forceinline__ int v_rd_base(int lane) { return ((lane & 3) << 3) | (((lane >> 2) & 3) << 6) | (((lane >> 4) & 1) << 5) | (((lane >> 5) & 1) << 8); }
; #define DMAV(t, b) do { DMA1(t, b, 2); DMA1(t, b, 3); } while (0)
; #define LANDED() do { asm volatile("s_waitcnt vmcnt(0)" ::: "memory"); __syncthreads(); } while (0)
; #define BLK_X(N0, N1, P0, P1, alP, t) do { SBAR(); __builtin_amdgcn_s_setprio(1); qkt(N0, N1, KBUF((t) & 3), qr, r32, hi, mapB); \
;     if constexpr (!SH) v_frag_read<0>(vfa, VBUF(((t) - 1) & 3)); \
;     finishSM<SH>(P0, P1, alP, l_reg, pa0, pa1, pa2, pa3); __builtin_amdgcn_s_setprio(0); SBAR(); } while (0)
; template <bool SH> __device__ __forceinline__ void attn_unit(bf16_t* __restrict__ proj, int tok0, int kv0, int seq, int h, float lam, float oscale, const float* __restrict__ subg, char* lds, bool dry) {
;     ...
;   const bf16_t* Qw = proj + (size_t)(tok0 + wq * 32 + r32) * NPROJ + C_Q + h * 128 + mp * 64 + hi * 8;
; #pragma unroll
;   for (int d0 = 0; d0 < 4; ++d0) qr[d0] = *reinterpret_cast<const bf16x8*>(Qw + d0 * 16);
;   unsigned vk0, vv0;
;   { const int c = tid;
;     { const int row = c >> 4, pc = c & 15, scn = pc ^ (row & 7); vk0 = (unsigned)(row * LDK + scn * 8) * 2u; }
;     { const int sub = c >> 5, kk = (sub >> 2) * 8 + ((c >> 2) & 7), col = (sub & 3) * 32 + (c & 3) * 8; vv0 = (unsigned)(kk * LDK + col) * 2u; } }
;   const unsigned ldsb = (unsigned)(uintptr_t)ldsl;
;   const int vbb = (int)(uintptr_t)ldsl + 16384 + v_rd_base(lane);
;     ...
;   DMA(0, 0); LANDED();
;   DMA(1, 1);
;   if (ty == 0) {
;     qkt(pA0, pA1, KBUF(0), qr, r32, hi, mapB); partialSM<SH>(pA0, pA1, m_reg, mnA, alA);
;     LANDED();
;     for (int j = 1; j + 1 < NT; j += 2) {
;       BLK_X(pB0, pB1, pA0, pA1, alA, j); DMAV(j + 1, (j + 1) & 3); BLK_Y(pB0, pB1, mnB, alB, j - 1); LANDED();
;       BLK_X(pA0, pA1, pB0, pB1, alB, j + 1); DMAV(j + 2, (j + 2) & 3); BLK_Y(pA0, pA1, mnA, alA, j); LANDED();
;     }
;     BLK_X(pB0, pB1, pA0, pA1, alA, NT - 1); BLK_Y(pB0, pB1, mnB, alB, NT - 2);
;     finishSM<SH>(pB0, pB1, alB, l_reg, pa0, pa1, pa2, pa3); SBAR();
;     if constexpr (SH) pv_d0(o, VBUF((NT - 1) & 3), pa0, pa1, pa2, pa3); else pv_d0_pipe<false>(o, VBUF((NT - 1) & 3), pa0, pa1, pa2, pa3, vfa);
;   } else {
;     qkt(pA0, pA1, KBUF(0), qr, r32, hi, mapB);
;     LANDED();
.LBB0_353:
	v_mov_b32_e32 v182, v184
	s_mov_b32 s59, s81
	v_readfirstlane_b32 s14, v182
	s_ashr_i32 s17, s14, 6
	s_and_b32 s15, s17, 3
	s_ashr_i32 s16, s14, 8
	s_lshl_b64 s[6:7], s[58:59], 1
	s_add_u32 s8, s68, s6
	s_addc_u32 s9, s69, s7
	s_lshl_b32 s0, s15, 5
	v_and_b32_e32 v205, 31, v182
	s_add_i32 s0, s0, s3
	v_add_u32_e32 v2, s0, v205
	v_mov_b64_e32 v[0:1], s[68:69]
	v_mad_i64_i32 v[0:1], s[0:1], v2, s25, v[0:1]
	s_lshl_b32 s4, s96, 1
	s_mov_b32 s5, s81
	s_lshl_b32 s0, s16, 6
	v_bfe_u32 v204, v182, 5, 1
	v_lshl_add_u64 v[0:1], v[0:1], 0, s[4:5]
	s_ashr_i32 s1, s0, 31
	v_lshl_add_u64 v[0:1], s[0:1], 1, v[0:1]
	v_lshlrev_b32_e32 v252, 4, v204
	v_lshl_add_u64 v[0:1], v[0:1], 0, v[252:253]
	global_load_dwordx4 v[140:143], v[0:1], off offset:3072
	global_load_dwordx4 v[136:139], v[0:1], off offset:3104
	global_load_dwordx4 v[132:135], v[0:1], off offset:3136
	global_load_dwordx4 v[128:131], v[0:1], off offset:3168
	s_add_u32 s20, s8, s4
	s_addc_u32 s21, s9, 0
	s_add_u32 s10, s20, 0x1000
	v_ashrrev_i32_e32 v0, 4, v182
	v_and_b32_e32 v1, 15, v182
	s_addc_u32 s11, s21, 0
	v_bitop3_b32 v1, v0, v1, 15 bitop3:0x6c
	v_mul_lo_u32 v2, v0, s25
	v_ashrrev_i32_e32 v183, 2, v182
	s_add_u32 s8, s20, 0x1400
	v_lshl_or_b32 v166, v1, 4, v2
	v_and_b32_e32 v1, 7, v183
	s_mov_b32 s0, 0x3ffff8
	s_addc_u32 s9, s21, 0
	v_and_or_b32 v0, v0, s0, v1
	v_and_b32_e32 v202, 3, v182
	s_add_i32 s18, 0, 0x4000
	v_and_b32_e32 v1, 0x60, v182
	v_lshlrev_b32_e32 v2, 3, v202
	v_mul_u32_u24_e32 v0, 0xc00, v0
	s_add_u32 s0, s20, 0x31000
	v_and_b32_e32 v203, 63, v182
	v_or3_b32 v0, v2, v1, v0
	v_lshlrev_b32_e32 v1, 4, v182
	s_addc_u32 s1, s21, 0
	v_lshlrev_b32_e32 v207, 1, v0
	v_lshlrev_b32_e32 v0, 3, v203
	v_and_b32_e32 v1, 0xc0, v1
	v_lshlrev_b32_e32 v2, 1, v182
	s_add_u32 s12, s20, 0x31400
	v_and_or_b32 v1, v0, 24, v1
	v_and_b32_e32 v2, 32, v2
	v_and_b32_e32 v0, 0x100, v0
	s_addc_u32 s13, s21, 0
	s_lshl_b32 s17, s17, 10
	v_or3_b32 v206, v1, v2, v0
	s_add_i32 s5, s17, 0
	v_add_u32_e32 v208, s18, v206
	s_add_i32 s19, s5, 0x2000
	s_add_i32 s18, s17, s18
	s_add_i32 s26, s5, 0x6000
	s_mov_b32 s27, m0
	s_mov_b32 m0, s5
	s_nop 0
	global_load_lds_dwordx4 v166, s[10:11]
	s_mov_b32 m0, s19
	s_nop 0
	global_load_lds_dwordx4 v166, s[0:1]
	s_mov_b32 m0, s18
	s_nop 0
	global_load_lds_dwordx4 v207, s[8:9]
	s_mov_b32 m0, s26
	s_nop 0
	global_load_lds_dwordx4 v207, s[12:13]
	s_mov_b32 m0, s27
	s_add_u32 s0, s20, 0x61000
	s_addc_u32 s1, s21, 0
	s_add_u32 s12, s20, 0x61400
	s_addc_u32 s13, s21, 0
	s_add_u32 s18, s20, 0x91000
	s_addc_u32 s19, s21, 0
	s_add_u32 s20, s20, 0x91400
	s_addc_u32 s21, s21, 0
	s_add_i32 s26, s5, 0x8000
	s_add_i32 s27, s5, 0xa000
	s_add_i32 s58, s5, 0xc000
	s_add_i32 s59, s5, 0xe000
	s_mov_b32 s60, m0
	s_mov_b32 m0, s26
	s_nop 0
	global_load_lds_dwordx4 v166, s[0:1]
	s_mov_b32 m0, s27
	s_nop 0
	global_load_lds_dwordx4 v166, s[18:19]
	s_mov_b32 m0, s58
	s_nop 0
	global_load_lds_dwordx4 v207, s[12:13]
	s_mov_b32 m0, s59
	s_nop 0
	global_load_lds_dwordx4 v207, s[20:21]
	s_mov_b32 m0, s60
	s_waitcnt vmcnt(4)
	s_barrier
	s_cmpk_lt_u32 s14, 0x100
	s_cselect_b64 s[0:1], -1, 0
	s_cmpk_gt_u32 s14, 0xff
	s_mov_b64 s[12:13], -1
	v_lshlrev_b32_e32 v209, 8, v205
	v_lshlrev_b32_e32 v210, 4, v205
	s_cbranch_scc0 .LBB0_357
	s_lshl_b32 s12, s16, 7
	v_and_b32_e32 v41, 0xf0, v210
	v_bitop3_b32 v167, s12, v41, v252 bitop3:0x36
	v_add_u32_e32 v165, v167, v209
	v_add_u32_e32 v42, 0, v165
	ds_read_b128 v[0:3], v42
	ds_read_b128 v[16:19], v42 offset:8192
	v_or_b32_e32 v40, s12, v252
	v_bitop3_b32 v168, v40, v41, 32 bitop3:0x36
	s_waitcnt vmcnt(3) lgkmcnt(1)
	v_mfma_f32_32x32x16_bf16 v[0:15], v[0:3], v[140:143], 0
	v_add_u32_e32 v164, v168, v209
	v_add_u32_e32 v43, 0, v164
	ds_read_b128 v[32:35], v43
	ds_read_b128 v[36:39], v43 offset:8192
	v_bitop3_b32 v169, v40, v41, 64 bitop3:0x36
	v_add_u32_e32 v163, v169, v209
	v_add_u32_e32 v44, 0, v163
	s_movk_i32 s12, 0x60
	s_waitcnt lgkmcnt(2)
	v_mfma_f32_32x32x16_bf16 v[16:31], v[16:19], v[140:143], 0
	v_bitop3_b32 v170, v40, v41, s12 bitop3:0x36
	v_add_u32_e32 v162, v170, v209
	v_add_u32_e32 v40, 0, v162
	s_add_u32 s12, s10, 0xc0000
	s_addc_u32 s13, s11, 0
	s_add_u32 s20, s8, 0xc0000
	s_addc_u32 s21, s9, 0
	s_waitcnt vmcnt(2) lgkmcnt(1)
	v_mfma_f32_32x32x16_bf16 v[0:15], v[32:35], v[136:139], v[0:15]
	s_add_u32 s26, s10, 0xf0000
	s_addc_u32 s27, s11, 0
	s_add_u32 s58, s8, 0xf0000
	s_addc_u32 s59, s9, 0
	s_add_i32 s19, s5, 0x10000
	s_add_i32 s60, s5, 0x12000
	s_add_i32 s61, s5, 0x14000
	s_waitcnt lgkmcnt(0)
	v_mfma_f32_32x32x16_bf16 v[16:31], v[36:39], v[136:139], v[16:31]
	ds_read_b128 v[32:35], v44
	ds_read_b128 v[36:39], v44 offset:8192
	s_add_i32 s64, s5, 0x16000
	s_mov_b32 s18, 4
	s_waitcnt vmcnt(1) lgkmcnt(1)
	v_mfma_f32_32x32x16_bf16 v[0:15], v[32:35], v[132:135], v[0:15]
	s_waitcnt lgkmcnt(0)
	v_mfma_f32_32x32x16_bf16 v[16:31], v[36:39], v[132:135], v[16:31]
	ds_read_b128 v[32:35], v40
	ds_read_b128 v[36:39], v40 offset:8192
	s_waitcnt vmcnt(0)
	s_waitcnt lgkmcnt(0)
	s_barrier
; #define PK4(P, BASE, OUT) do { u32x4 w = {cvtpk_b(P[BASE + 0], P[BASE + 1]), cvtpk_b(P[BASE + 2], P[BASE + 3]), cvtpk_b(P[BASE + 4], P[BASE + 5]), cvtpk_b(P[BASE + 6], P[BASE + 7])}; \
;     OUT = *reinterpret_cast<bf16x8*>(&w); } while (0)
; #define LANDED() do { asm volatile("s_waitcnt vmcnt(0)" ::: "memory"); __syncthreads(); } while (0)
; #define BLK_X(N0, N1, P0, P1, alP, t) do { SBAR(); __builtin_amdgcn_s_setprio(1); qkt(N0, N1, KBUF((t) & 3), qr, r32, hi, mapB); \
;     if constexpr (!SH) v_frag_read<0>(vfa, VBUF(((t) - 1) & 3)); \
;     finishSM<SH>(P0, P1, alP, l_reg, pa0, pa1, pa2, pa3); __builtin_amdgcn_s_setprio(0); SBAR(); } while (0)
; template <bool SH> __device__ __forceinline__ void finishSM(f32x16& p0, f32x16& p1, float alpha, float& l_reg, bf16x8& pa0, bf16x8& pa1, bf16x8& pa2, bf16x8& pa3) {
;   if constexpr (!SH) {
; #pragma unroll
;     for (int r = 0; r < 16; ++r) { p0[r] = __builtin_amdgcn_exp2f(p0[r]); p1[r] = __builtin_amdgcn_exp2f(p1[r]); }
;   }
;   float ps = 0;
; #pragma unroll
;   for (int r = 0; r < 16; ++r) ps += p0[r];
; #pragma unroll
;   for (int r = 0; r < 16; ++r) ps += p1[r];
;   if constexpr (SH) l_reg = l_reg * alpha + ps; else l_reg += ps;
;     ...
;   PK4(p0, 0, pa0); PK4(p0, 8, pa1); PK4(p1, 0, pa2); PK4(p1, 8, pa3);
;     ...
; }
; __device__ __forceinline__ void qkt(f32x16& p0, f32x16& p1, const char* Ks, const bf16x8* qr, int r32, int hi, int mapB) {
;   p0 = f32x16{}; p1 = f32x16{};
; #pragma unroll
;   for (int d0 = 0; d0 < 4; ++d0) { const int cb = (d0 * 16 + hi * 8) * 2 + mapB;
;     bf16x8 b0 = *reinterpret_cast<const bf16x8*>(Ks + KSWZ(r32, cb));
;     bf16x8 b1 = *reinterpret_cast<const bf16x8*>(Ks + KSWZ(32 + r32, cb));
;     p0 = __builtin_amdgcn_mfma_f32_32x32x16_bf16(b0, qr[d0], p0, 0, 0, 0);
;     p1 = __builtin_amdgcn_mfma_f32_32x32x16_bf16(b1, qr[d0], p1, 0, 0, 0); }
; }
; template <bool SH> __device__ __forceinline__ void attn_unit(bf16_t* __restrict__ proj, int tok0, int kv0, int seq, int h, float lam, float oscale, const float* __restrict__ subg, char* lds, bool dry) {
;     ...
;     DMA(2, 2); DMA1X(2, 2, 0, wid - 4); DMA1X(2, 2, 1, wid - 4); partialSM<SH>(pA0, pA1, m_reg, mnA, alA); BLK_X(pB0, pB1, pA0, pA1, alA, 1); LANDED();
	s_mov_b32 s65, m0
	s_mov_b32 m0, s19
	s_nop 0
	global_load_lds_dwordx4 v166, s[12:13]
	s_mov_b32 m0, s60
	s_nop 0
	global_load_lds_dwordx4 v166, s[26:27]
	s_mov_b32 m0, s61
	s_nop 0
	global_load_lds_dwordx4 v207, s[20:21]
	s_mov_b32 m0, s64
	s_nop 0
	global_load_lds_dwordx4 v207, s[58:59]
	s_mov_b32 m0, s65
	s_add_u32 s12, s10, 0xa8000
	s_waitcnt vmcnt(0)
	v_mfma_f32_32x32x16_bf16 v[0:15], v[32:35], v[128:131], v[0:15]
	s_addc_u32 s13, s11, 0
	s_add_i32 s19, s17, 0xfffff000
	s_add_i32 s20, s5, 0xf000
	s_setprio 3
	s_mov_b32 s21, m0
	s_mov_b32 m0, s20
	s_nop 0
	global_load_lds_dwordx4 v166, s[12:13]
	s_mov_b32 m0, s21
	s_setprio 0
	s_add_u32 s12, s10, 0xd8000
	s_addc_u32 s13, s11, 0
	s_add_i32 s20, s5, 0x11000
	v_mfma_f32_32x32x16_bf16 v[16:31], v[36:39], v[128:131], v[16:31]
	s_setprio 3
	s_mov_b32 s21, m0
	s_mov_b32 m0, s20
	s_nop 0
	global_load_lds_dwordx4 v166, s[12:13]
	s_mov_b32 m0, s21
	s_setprio 0
	s_setprio 1
	ds_read_b128 v[32:35], v42 offset:32768
	ds_read_b128 v[36:39], v42 offset:40960
	s_waitcnt lgkmcnt(1)
	v_mfma_f32_32x32x16_bf16 v[64:79], v[32:35], v[140:143], 0
	s_waitcnt lgkmcnt(0)
	v_mfma_f32_32x32x16_bf16 v[80:95], v[36:39], v[140:143], 0
	ds_read_b128 v[32:35], v43 offset:32768
	ds_read_b128 v[36:39], v43 offset:40960
	s_waitcnt lgkmcnt(1)
	v_mfma_f32_32x32x16_bf16 v[64:79], v[32:35], v[136:139], v[64:79]
	s_waitcnt lgkmcnt(0)
	v_mfma_f32_32x32x16_bf16 v[80:95], v[36:39], v[136:139], v[80:95]
	ds_read_b128 v[32:35], v44 offset:32768
	ds_read_b128 v[36:39], v44 offset:40960
	s_waitcnt lgkmcnt(1)
	v_mfma_f32_32x32x16_bf16 v[64:79], v[32:35], v[132:135], v[64:79]
	s_waitcnt lgkmcnt(0)
	v_mfma_f32_32x32x16_bf16 v[80:95], v[36:39], v[132:135], v[80:95]
	ds_read_b128 v[32:35], v40 offset:32768
	ds_read_b128 v[36:39], v40 offset:40960
	ds_read_b64_tr_b16 v[156:157], v208 offset:0
	ds_read_b64_tr_b16 v[158:159], v208 offset:0x800
	ds_read_b64_tr_b16 v[152:153], v208 offset:0x1000
	ds_read_b64_tr_b16 v[154:155], v208 offset:0x1800
	ds_read_b64_tr_b16 v[148:149], v208 offset:0x2000
	ds_read_b64_tr_b16 v[150:151], v208 offset:0x2800
	s_waitcnt lgkmcnt(1)
	v_mfma_f32_32x32x16_bf16 v[64:79], v[32:35], v[128:131], v[64:79]
	ds_read_b64_tr_b16 v[144:145], v208 offset:0x3000
	ds_read_b64_tr_b16 v[146:147], v208 offset:0x3800
	s_waitcnt lgkmcnt(0)
	v_mfma_f32_32x32x16_bf16 v[80:95], v[36:39], v[128:131], v[80:95]
	s_setprio 0
	v_exp_f32_e32 v0, v0
	v_exp_f32_e32 v1, v1
	v_exp_f32_e32 v2, v2
	v_exp_f32_e32 v3, v3
	v_exp_f32_e32 v4, v4
	v_add_f32_e32 v32, 0, v0
	v_exp_f32_e32 v5, v5
	v_add_f32_e32 v32, v1, v32
	v_exp_f32_e32 v6, v6
	v_add_f32_e32 v32, v2, v32
	v_exp_f32_e32 v7, v7
	v_add_f32_e32 v32, v3, v32
	v_exp_f32_e32 v8, v8
	v_add_f32_e32 v32, v4, v32
	v_exp_f32_e32 v9, v9
	v_add_f32_e32 v32, v5, v32
	v_exp_f32_e32 v10, v10
	v_add_f32_e32 v32, v6, v32
	v_exp_f32_e32 v11, v11
	v_add_f32_e32 v32, v7, v32
	v_exp_f32_e32 v12, v12
	v_add_f32_e32 v32, v8, v32
	v_exp_f32_e32 v13, v13
	v_add_f32_e32 v32, v9, v32
	v_exp_f32_e32 v14, v14
	v_add_f32_e32 v32, v10, v32
	v_exp_f32_e32 v15, v15
	v_add_f32_e32 v32, v11, v32
	v_exp_f32_e32 v16, v16
	v_add_f32_e32 v32, v12, v32
	v_exp_f32_e32 v17, v17
	v_add_f32_e32 v32, v13, v32
	v_exp_f32_e32 v18, v18
	v_add_f32_e32 v32, v14, v32
	v_exp_f32_e32 v19, v19
	v_add_f32_e32 v32, v15, v32
	v_exp_f32_e32 v20, v20
	v_add_f32_e32 v32, v16, v32
	v_exp_f32_e32 v21, v21
	v_add_f32_e32 v32, v17, v32
	v_exp_f32_e32 v22, v22
	v_add_f32_e32 v32, v18, v32
	v_exp_f32_e32 v23, v23
	v_add_f32_e32 v32, v19, v32
	v_exp_f32_e32 v24, v24
	v_add_f32_e32 v32, v20, v32
	v_exp_f32_e32 v25, v25
	v_add_f32_e32 v32, v21, v32
	v_exp_f32_e32 v26, v26
	v_add_f32_e32 v32, v22, v32
	v_exp_f32_e32 v27, v27
	v_add_f32_e32 v32, v23, v32
	v_exp_f32_e32 v28, v28
	v_add_f32_e32 v32, v24, v32
	v_exp_f32_e32 v29, v29
	v_add_f32_e32 v32, v25, v32
	v_exp_f32_e32 v30, v30
	v_add_f32_e32 v32, v26, v32
	v_exp_f32_e32 v31, v31
	v_add_f32_e32 v32, v27, v32
	v_add_f32_e32 v32, v28, v32
	v_add_f32_e32 v32, v29, v32
	s_add_u32 s12, s80, s6
	s_waitcnt vmcnt(0)
	v_add_f32_e32 v32, v30, v32
	s_addc_u32 s13, 0, s7
	v_readlane_b32 s20, v255, 6
	v_add_f32_e32 v32, v31, v32
	s_add_u32 s12, s20, s12
	v_readlane_b32 s20, v255, 8
	v_mov_b32_e32 v48, 0
	v_add_f32_e32 v171, 0, v32
	v_cvt_pk_bf16_f32 v108, v0, v1
	v_cvt_pk_bf16_f32 v109, v2, v3
	v_cvt_pk_bf16_f32 v110, v4, v5
	v_cvt_pk_bf16_f32 v111, v6, v7
	v_cvt_pk_bf16_f32 v104, v8, v9
	v_cvt_pk_bf16_f32 v105, v10, v11
	v_cvt_pk_bf16_f32 v106, v12, v13
	v_cvt_pk_bf16_f32 v107, v14, v15
	v_cvt_pk_bf16_f32 v100, v16, v17
	v_cvt_pk_bf16_f32 v101, v18, v19
	v_cvt_pk_bf16_f32 v102, v20, v21
	v_cvt_pk_bf16_f32 v103, v22, v23
	v_cvt_pk_bf16_f32 v96, v24, v25
	v_cvt_pk_bf16_f32 v97, v26, v27
	v_cvt_pk_bf16_f32 v98, v28, v29
	v_cvt_pk_bf16_f32 v99, v30, v31
	s_addc_u32 s13, s20, s13
	s_mov_b32 s20, 0x18000
	v_mov_b32_e32 v49, v48
	v_mov_b32_e32 v50, v48
	v_mov_b32_e32 v51, v48
	v_mov_b32_e32 v52, v48
	v_mov_b32_e32 v53, v48
	v_mov_b32_e32 v54, v48
	v_mov_b32_e32 v55, v48
	v_mov_b32_e32 v56, v48
	v_mov_b32_e32 v57, v48
	v_mov_b32_e32 v58, v48
	v_mov_b32_e32 v59, v48
	v_mov_b32_e32 v60, v48
	v_mov_b32_e32 v61, v48
	v_mov_b32_e32 v62, v48
	v_mov_b32_e32 v63, v48
	v_mov_b32_e32 v32, v48
	v_mov_b32_e32 v33, v48
	v_mov_b32_e32 v34, v48
	v_mov_b32_e32 v35, v48
	v_mov_b32_e32 v36, v48
	v_mov_b32_e32 v37, v48
	v_mov_b32_e32 v38, v48
	v_mov_b32_e32 v39, v48
	v_mov_b32_e32 v40, v48
	v_mov_b32_e32 v41, v48
	v_mov_b32_e32 v42, v48
	v_mov_b32_e32 v43, v48
	v_mov_b32_e32 v44, v48
	v_mov_b32_e32 v45, v48
	v_mov_b32_e32 v46, v48
	v_mov_b32_e32 v47, v48
	v_mov_b32_e32 v16, v48
	v_mov_b32_e32 v17, v48
	v_mov_b32_e32 v18, v48
	v_mov_b32_e32 v19, v48
	v_mov_b32_e32 v20, v48
	v_mov_b32_e32 v21, v48
	v_mov_b32_e32 v22, v48
	v_mov_b32_e32 v23, v48
	v_mov_b32_e32 v24, v48
	v_mov_b32_e32 v25, v48
	v_mov_b32_e32 v26, v48
	v_mov_b32_e32 v27, v48
	v_mov_b32_e32 v28, v48
	v_mov_b32_e32 v29, v48
	v_mov_b32_e32 v30, v48
	v_mov_b32_e32 v31, v48
	v_mov_b32_e32 v0, v48
	v_mov_b32_e32 v1, v48
	v_mov_b32_e32 v2, v48
	v_mov_b32_e32 v3, v48
	v_mov_b32_e32 v4, v48
	v_mov_b32_e32 v5, v48
	v_mov_b32_e32 v6, v48
	v_mov_b32_e32 v7, v48
	v_mov_b32_e32 v8, v48
	v_mov_b32_e32 v9, v48
	v_mov_b32_e32 v10, v48
	v_mov_b32_e32 v11, v48
	v_mov_b32_e32 v12, v48
	v_mov_b32_e32 v13, v48
	v_mov_b32_e32 v14, v48
	v_mov_b32_e32 v15, v48
	s_barrier
; __device__ __forceinline__ void qkt_k(f32x16& p0, f32x16& p1, const char* Ks, const bf16x8* kf, const bf16x8* qr, int r32, int hi, int mapB) {
;   p0 = f32x16{}; p1 = f32x16{};
;   p0 = __builtin_amdgcn_mfma_f32_32x32x16_bf16(kf[0], qr[0], p0, 0, 0, 0);
;   p1 = __builtin_amdgcn_mfma_f32_32x32x16_bf16(kf[1], qr[0], p1, 0, 0, 0);
; #pragma unroll
;   for (int d0 = 1; d0 < 4; ++d0) { const int cb = (d0 * 16 + hi * 8) * 2 + mapB;
;     bf16x8 b0 = *reinterpret_cast<const bf16x8*>(Ks + KSWZ(r32, cb));
;     bf16x8 b1 = *reinterpret_cast<const bf16x8*>(Ks + KSWZ(32 + r32, cb));
;     p0 = __builtin_amdgcn_mfma_f32_32x32x16_bf16(b0, qr[d0], p0, 0, 0, 0);
;     p1 = __builtin_amdgcn_mfma_f32_32x32x16_bf16(b1, qr[d0], p1, 0, 0, 0); }
; }
.LBB0_355:
	s_add_i32 s21, s20, 0xffff8000
	s_waitcnt lgkmcnt(0)
	s_and_b32 s21, s21, 0x10000
	s_xor_b32 s26, s21, 0x10000
	v_add_u32_e32 v160, s26, v208
	ds_read_b64_tr_b16 v[112:113], v160 offset:0x200
	ds_read_b64_tr_b16 v[114:115], v160 offset:0xa00
	ds_read_b64_tr_b16 v[116:117], v160 offset:0x1200
	ds_read_b64_tr_b16 v[118:119], v160 offset:0x1a00
	ds_read_b64_tr_b16 v[120:121], v160 offset:0x2200
	ds_read_b64_tr_b16 v[122:123], v160 offset:0x2a00
	ds_read_b64_tr_b16 v[124:125], v160 offset:0x3200
	ds_read_b64_tr_b16 v[126:127], v160 offset:0x3a00
	v_mfma_f32_32x32x16_bf16 v[48:63], v[108:111], v[156:159], v[48:63]
	s_and_b32 s27, s20, 0x18000
	s_add_i32 s27, s27, 0
	s_add_i32 s26, s27, s17
	s_setprio 3
	s_mov_b32 s58, m0
	s_mov_b32 m0, s26
	s_nop 0
	global_load_lds_dwordx4 v166, s[12:13]
	s_mov_b32 m0, s58
	s_setprio 0
	s_add_u32 s58, s12, 0xfffe8000
	s_addc_u32 s59, s13, -1
	s_add_i32 s60, s27, s19
	v_mfma_f32_32x32x16_bf16 v[48:63], v[104:107], v[152:155], v[48:63]
	s_setprio 3
	s_mov_b32 s61, m0
	s_mov_b32 m0, s60
	s_nop 0
	global_load_lds_dwordx4 v166, s[58:59]
	s_mov_b32 m0, s61
	s_setprio 0
	v_mfma_f32_32x32x16_bf16 v[48:63], v[100:103], v[148:151], v[48:63]
	v_mfma_f32_32x32x16_bf16 v[48:63], v[96:99], v[144:147], v[48:63]
	s_waitcnt lgkmcnt(0)
	ds_read_b64_tr_b16 v[144:145], v160 offset:0x400
	ds_read_b64_tr_b16 v[146:147], v160 offset:0xc00
	ds_read_b64_tr_b16 v[148:149], v160 offset:0x1400
	ds_read_b64_tr_b16 v[150:151], v160 offset:0x1c00
	ds_read_b64_tr_b16 v[152:153], v160 offset:0x2400
	ds_read_b64_tr_b16 v[154:155], v160 offset:0x2c00
	ds_read_b64_tr_b16 v[156:157], v160 offset:0x3400
	ds_read_b64_tr_b16 v[158:159], v160 offset:0x3c00
	v_mfma_f32_32x32x16_bf16 v[32:47], v[108:111], v[112:115], v[32:47]
	s_add_u32 s58, s12, 0x30000
	s_addc_u32 s59, s13, 0
	s_add_i32 s61, s26, 0x2000
	s_setprio 3
	s_mov_b32 s64, m0
	s_mov_b32 m0, s61
	s_nop 0
	global_load_lds_dwordx4 v166, s[58:59]
	s_mov_b32 m0, s64
	s_setprio 0
	s_add_u32 s58, s12, 0x18000
	s_addc_u32 s59, s13, 0
	s_addk_i32 s60, 0x2000
	v_mfma_f32_32x32x16_bf16 v[32:47], v[104:107], v[116:119], v[32:47]
	s_setprio 3
	s_mov_b32 s61, m0
	s_mov_b32 m0, s60
	s_nop 0
	global_load_lds_dwordx4 v166, s[58:59]
	s_mov_b32 m0, s61
	s_setprio 0
	v_mfma_f32_32x32x16_bf16 v[32:47], v[100:103], v[120:123], v[32:47]
	v_mfma_f32_32x32x16_bf16 v[32:47], v[96:99], v[124:127], v[32:47]
	s_waitcnt lgkmcnt(0)
	ds_read_b64_tr_b16 v[112:113], v160 offset:0x600
	ds_read_b64_tr_b16 v[114:115], v160 offset:0xe00
	ds_read_b64_tr_b16 v[116:117], v160 offset:0x1600
	ds_read_b64_tr_b16 v[118:119], v160 offset:0x1e00
	ds_read_b64_tr_b16 v[120:121], v160 offset:0x2600
	ds_read_b64_tr_b16 v[122:123], v160 offset:0x2e00
	ds_read_b64_tr_b16 v[124:125], v160 offset:0x3600
	ds_read_b64_tr_b16 v[126:127], v160 offset:0x3e00
	v_mfma_f32_32x32x16_bf16 v[16:31], v[108:111], v[144:147], v[16:31]
	s_add_u32 s58, s12, 0x400
	s_addc_u32 s59, s13, 0
	s_add_i32 s60, s26, 0x4000
	s_setprio 3
	s_mov_b32 s61, m0
	s_mov_b32 m0, s60
	s_nop 0
	global_load_lds_dwordx4 v207, s[58:59]
	s_mov_b32 m0, s61
	s_setprio 0
	v_mfma_f32_32x32x16_bf16 v[16:31], v[104:107], v[148:151], v[16:31]
	v_mfma_f32_32x32x16_bf16 v[16:31], v[100:103], v[152:155], v[16:31]
	v_mfma_f32_32x32x16_bf16 v[16:31], v[96:99], v[156:159], v[16:31]
	s_waitcnt lgkmcnt(0)
	v_mfma_f32_32x32x16_bf16 v[0:15], v[108:111], v[112:115], v[0:15]
	s_add_u32 s58, s12, 0x30400
	s_addc_u32 s59, s13, 0
	s_addk_i32 s26, 0x6000
	s_setprio 3
	s_mov_b32 s60, m0
	s_mov_b32 m0, s26
	s_nop 0
	global_load_lds_dwordx4 v207, s[58:59]
	s_mov_b32 m0, s60
	s_setprio 0
	s_add_i32 s26, s21, 0
	v_add_u32_e32 v160, s26, v165
	v_mfma_f32_32x32x16_bf16 v[0:15], v[104:107], v[116:119], v[0:15]
	v_mfma_f32_32x32x16_bf16 v[0:15], v[100:103], v[120:123], v[0:15]
	ds_read_b128 v[100:103], v160
	ds_read_b128 v[112:115], v160 offset:8192
	v_mfma_f32_32x32x16_bf16 v[0:15], v[96:99], v[124:127], v[0:15]
	s_setprio 2
	v_exp_f32_e32 v64, v64
	v_exp_f32_e32 v65, v65
	v_exp_f32_e32 v66, v66
	s_waitcnt lgkmcnt(1)
	v_mfma_f32_32x32x16_bf16 v[96:111], v[100:103], v[140:143], 0
	v_exp_f32_e32 v67, v67
	v_exp_f32_e32 v68, v68
	v_add_f32_e32 v172, 0, v64
	v_exp_f32_e32 v69, v69
	v_add_f32_e32 v172, v65, v172
	v_add_u32_e32 v148, s26, v164
	v_exp_f32_e32 v70, v70
	s_waitcnt lgkmcnt(0)
	v_mfma_f32_32x32x16_bf16 v[112:127], v[112:115], v[140:143], 0
	v_add_f32_e32 v172, v66, v172
	ds_read_b128 v[144:147], v148
	ds_read_b128 v[148:151], v148 offset:8192
	v_exp_f32_e32 v71, v71
	v_add_f32_e32 v172, v67, v172
	v_exp_f32_e32 v72, v72
	v_add_f32_e32 v172, v68, v172
	v_exp_f32_e32 v73, v73
	v_add_f32_e32 v172, v69, v172
	v_exp_f32_e32 v74, v74
	v_add_f32_e32 v172, v70, v172
	s_waitcnt lgkmcnt(1)
	v_mfma_f32_32x32x16_bf16 v[96:111], v[144:147], v[136:139], v[96:111]
	v_exp_f32_e32 v75, v75
	v_add_f32_e32 v172, v71, v172
	v_exp_f32_e32 v76, v76
	v_add_f32_e32 v172, v72, v172
	v_exp_f32_e32 v77, v77
	v_add_f32_e32 v172, v73, v172
	v_exp_f32_e32 v78, v78
	s_waitcnt lgkmcnt(0)
	v_mfma_f32_32x32x16_bf16 v[112:127], v[148:151], v[136:139], v[112:127]
	v_add_u32_e32 v148, s26, v163
	v_add_f32_e32 v172, v74, v172
	ds_read_b128 v[144:147], v148
	ds_read_b128 v[148:151], v148 offset:8192
	v_exp_f32_e32 v79, v79
	v_add_f32_e32 v172, v75, v172
	v_exp_f32_e32 v80, v80
	v_add_f32_e32 v172, v76, v172
	v_exp_f32_e32 v81, v81
	v_add_f32_e32 v172, v77, v172
	v_exp_f32_e32 v82, v82
	v_add_f32_e32 v172, v78, v172
	s_waitcnt lgkmcnt(1)
	v_mfma_f32_32x32x16_bf16 v[96:111], v[144:147], v[132:135], v[96:111]
	v_exp_f32_e32 v83, v83
	v_add_f32_e32 v172, v79, v172
	v_exp_f32_e32 v84, v84
	v_add_f32_e32 v172, v80, v172
	v_exp_f32_e32 v85, v85
	v_add_f32_e32 v172, v81, v172
	v_exp_f32_e32 v86, v86
	s_waitcnt lgkmcnt(0)
; __device__ __forceinline__ void qkt_k(f32x16& p0, f32x16& p1, const char* Ks, const bf16x8* kf, const bf16x8* qr, int r32, int hi, int mapB) {
;   p0 = f32x16{}; p1 = f32x16{};
;   p0 = __builtin_amdgcn_mfma_f32_32x32x16_bf16(kf[0], qr[0], p0, 0, 0, 0);
;   p1 = __builtin_amdgcn_mfma_f32_32x32x16_bf16(kf[1], qr[0], p1, 0, 0, 0);
; #pragma unroll
;   for (int d0 = 1; d0 < 4; ++d0) { const int cb = (d0 * 16 + hi * 8) * 2 + mapB;
;     bf16x8 b0 = *reinterpret_cast<const bf16x8*>(Ks + KSWZ(r32, cb));
;     bf16x8 b1 = *reinterpret_cast<const bf16x8*>(Ks + KSWZ(32 + r32, cb));
;     p0 = __builtin_amdgcn_mfma_f32_32x32x16_bf16(b0, qr[d0], p0, 0, 0, 0);
;     p1 = __builtin_amdgcn_mfma_f32_32x32x16_bf16(b1, qr[d0], p1, 0, 0, 0); }
; }
	v_mfma_f32_32x32x16_bf16 v[112:127], v[148:151], v[132:135], v[112:127]
	v_add_u32_e32 v148, s26, v162
	v_add_f32_e32 v172, v82, v172
	ds_read_b128 v[144:147], v148
	ds_read_b128 v[148:151], v148 offset:8192
	v_exp_f32_e32 v87, v87
	v_add_f32_e32 v172, v83, v172
	v_exp_f32_e32 v88, v88
	v_add_f32_e32 v172, v84, v172
	s_add_i32 s26, s20, 0x10000
	v_exp_f32_e32 v89, v89
	v_add_f32_e32 v172, v85, v172
	s_and_b32 s58, s26, 0x18000
	v_exp_f32_e32 v90, v90
	v_add_f32_e32 v172, v86, v172
	s_waitcnt lgkmcnt(1)
	v_mfma_f32_32x32x16_bf16 v[96:111], v[144:147], v[128:131], v[96:111]
	v_add_u32_e32 v161, s58, v208
	ds_read_b64_tr_b16 v[144:145], v161 offset:0
	v_exp_f32_e32 v91, v91
	v_add_f32_e32 v172, v87, v172
	ds_read_b64_tr_b16 v[146:147], v161 offset:0x800
	v_exp_f32_e32 v92, v92
	v_add_f32_e32 v172, v88, v172
	s_waitcnt lgkmcnt(0)
	v_mfma_f32_32x32x16_bf16 v[112:127], v[148:151], v[128:131], v[112:127]
	ds_read_b64_tr_b16 v[148:149], v161 offset:0x1000
	v_exp_f32_e32 v93, v93
	v_add_f32_e32 v172, v89, v172
	ds_read_b64_tr_b16 v[150:151], v161 offset:0x1800
	v_exp_f32_e32 v94, v94
	v_add_f32_e32 v172, v90, v172
	ds_read_b64_tr_b16 v[152:153], v161 offset:0x2000
	v_exp_f32_e32 v95, v95
	v_add_f32_e32 v172, v91, v172
	ds_read_b64_tr_b16 v[154:155], v161 offset:0x2800
	v_add_f32_e32 v172, v92, v172
	ds_read_b64_tr_b16 v[156:157], v161 offset:0x3000
	v_add_f32_e32 v172, v93, v172
	ds_read_b64_tr_b16 v[158:159], v161 offset:0x3800
	v_add_f32_e32 v172, v94, v172
	v_add_f32_e32 v172, v95, v172
	v_add_f32_e32 v171, v171, v172
	v_cvt_pk_bf16_f32 v64, v64, v65
	v_cvt_pk_bf16_f32 v65, v66, v67
	v_cvt_pk_bf16_f32 v66, v68, v69
	v_cvt_pk_bf16_f32 v67, v70, v71
	v_cvt_pk_bf16_f32 v68, v72, v73
	v_cvt_pk_bf16_f32 v69, v74, v75
	v_cvt_pk_bf16_f32 v70, v76, v77
	v_cvt_pk_bf16_f32 v71, v78, v79
	v_cvt_pk_bf16_f32 v72, v80, v81
	v_cvt_pk_bf16_f32 v73, v82, v83
	v_cvt_pk_bf16_f32 v74, v84, v85
	v_cvt_pk_bf16_f32 v75, v86, v87
	v_cvt_pk_bf16_f32 v76, v88, v89
	v_cvt_pk_bf16_f32 v77, v90, v91
	v_cvt_pk_bf16_f32 v78, v92, v93
	v_cvt_pk_bf16_f32 v79, v94, v95
	s_setprio 0
	s_waitcnt vmcnt(0)
	s_barrier
	s_waitcnt lgkmcnt(0)
	ds_read_b64_tr_b16 v[80:81], v161 offset:0x200
	ds_read_b64_tr_b16 v[82:83], v161 offset:0xa00
	ds_read_b64_tr_b16 v[84:85], v161 offset:0x1200
	ds_read_b64_tr_b16 v[86:87], v161 offset:0x1a00
	ds_read_b64_tr_b16 v[88:89], v161 offset:0x2200
	ds_read_b64_tr_b16 v[90:91], v161 offset:0x2a00
	ds_read_b64_tr_b16 v[92:93], v161 offset:0x3200
	ds_read_b64_tr_b16 v[94:95], v161 offset:0x3a00
	v_mfma_f32_32x32x16_bf16 v[48:63], v[64:67], v[144:147], v[48:63]
	s_add_u32 s58, s12, 0x60000
	s_addc_u32 s59, s13, 0
	s_add_i32 s20, s20, 0x8000
	s_and_b32 s20, s20, 0x10000
	s_add_i32 s20, s20, 0
	s_add_i32 s60, s20, s17
	s_setprio 3
	s_mov_b32 s61, m0
	s_mov_b32 m0, s60
	s_nop 0
	global_load_lds_dwordx4 v166, s[58:59]
	s_mov_b32 m0, s61
	s_setprio 0
	v_mfma_f32_32x32x16_bf16 v[48:63], v[68:71], v[148:151], v[48:63]
	s_add_u32 s58, s12, 0x48000
	s_addc_u32 s59, s13, 0
	s_add_i32 s20, s20, s19
	s_setprio 3
	s_mov_b32 s61, m0
	s_mov_b32 m0, s20
	s_nop 0
	global_load_lds_dwordx4 v166, s[58:59]
	s_mov_b32 m0, s61
	s_setprio 0
	v_mfma_f32_32x32x16_bf16 v[48:63], v[72:75], v[152:155], v[48:63]
	v_mfma_f32_32x32x16_bf16 v[48:63], v[76:79], v[156:159], v[48:63]
	s_waitcnt lgkmcnt(0)
	ds_read_b64_tr_b16 v[144:145], v161 offset:0x400
	ds_read_b64_tr_b16 v[146:147], v161 offset:0xc00
	ds_read_b64_tr_b16 v[148:149], v161 offset:0x1400
	ds_read_b64_tr_b16 v[150:151], v161 offset:0x1c00
	ds_read_b64_tr_b16 v[152:153], v161 offset:0x2400
	ds_read_b64_tr_b16 v[154:155], v161 offset:0x2c00
	ds_read_b64_tr_b16 v[156:157], v161 offset:0x3400
	ds_read_b64_tr_b16 v[158:159], v161 offset:0x3c00
	v_mfma_f32_32x32x16_bf16 v[32:47], v[64:67], v[80:83], v[32:47]
	s_add_u32 s58, s12, 0x90000
	s_addc_u32 s59, s13, 0
	s_add_i32 s61, s60, 0x2000
	s_setprio 3
	s_mov_b32 s64, m0
	s_mov_b32 m0, s61
	s_nop 0
	global_load_lds_dwordx4 v166, s[58:59]
	s_mov_b32 m0, s64
	s_setprio 0
	s_add_u32 s58, s12, 0x78000
	s_addc_u32 s59, s13, 0
	s_addk_i32 s20, 0x2000
	v_mfma_f32_32x32x16_bf16 v[32:47], v[68:71], v[84:87], v[32:47]
	s_setprio 3
	s_mov_b32 s61, m0
	s_mov_b32 m0, s20
	s_nop 0
	global_load_lds_dwordx4 v166, s[58:59]
	s_mov_b32 m0, s61
	s_setprio 0
	v_mfma_f32_32x32x16_bf16 v[32:47], v[72:75], v[88:91], v[32:47]
	v_mfma_f32_32x32x16_bf16 v[32:47], v[76:79], v[92:95], v[32:47]
	s_waitcnt lgkmcnt(0)
	ds_read_b64_tr_b16 v[80:81], v161 offset:0x600
	ds_read_b64_tr_b16 v[82:83], v161 offset:0xe00
	ds_read_b64_tr_b16 v[84:85], v161 offset:0x1600
	ds_read_b64_tr_b16 v[86:87], v161 offset:0x1e00
	ds_read_b64_tr_b16 v[88:89], v161 offset:0x2600
	ds_read_b64_tr_b16 v[90:91], v161 offset:0x2e00
	ds_read_b64_tr_b16 v[92:93], v161 offset:0x3600
	ds_read_b64_tr_b16 v[94:95], v161 offset:0x3e00
	v_mfma_f32_32x32x16_bf16 v[16:31], v[64:67], v[144:147], v[16:31]
	s_add_u32 s58, s12, 0x60400
	s_addc_u32 s59, s13, 0
	s_add_i32 s20, s60, 0x4000
	s_setprio 3
	s_mov_b32 s61, m0
	s_mov_b32 m0, s20
	s_nop 0
	global_load_lds_dwordx4 v207, s[58:59]
	s_mov_b32 m0, s61
	s_setprio 0
	v_mfma_f32_32x32x16_bf16 v[16:31], v[68:71], v[148:151], v[16:31]
	v_mfma_f32_32x32x16_bf16 v[16:31], v[72:75], v[152:155], v[16:31]
	v_mfma_f32_32x32x16_bf16 v[16:31], v[76:79], v[156:159], v[16:31]
	s_waitcnt lgkmcnt(0)
	v_mfma_f32_32x32x16_bf16 v[0:15], v[64:67], v[80:83], v[0:15]
	s_add_u32 s58, s12, 0x90400
	s_addc_u32 s59, s13, 0
	s_addk_i32 s60, 0x6000
	s_setprio 3
	s_mov_b32 s20, m0
	s_mov_b32 m0, s60
	s_nop 0
	global_load_lds_dwordx4 v207, s[58:59]
	s_mov_b32 m0, s20
	s_setprio 0
	ds_read_b128 v[64:67], v160 offset:32768
	ds_read_b128 v[80:83], v160 offset:40960
	v_mfma_f32_32x32x16_bf16 v[0:15], v[68:71], v[84:87], v[0:15]
	v_mfma_f32_32x32x16_bf16 v[0:15], v[72:75], v[88:91], v[0:15]
	v_mfma_f32_32x32x16_bf16 v[0:15], v[76:79], v[92:95], v[0:15]
	s_setprio 2
	s_waitcnt lgkmcnt(0)
; #define LANDED() do { asm volatile("s_waitcnt vmcnt(0)" ::: "memory"); __syncthreads(); } while (0)
; #define BLK_XK(N0, N1, P0, P1, alP, t) do { SBAR(); __builtin_amdgcn_s_setprio(1); \
;     if constexpr (SH) qkt(N0, N1, KBUF((t) & 3), qr, r32, hi, mapB); else qkt_k(N0, N1, KBUF((t) & 3), kf, qr, r32, hi, mapB); \
;     if constexpr (!SH) v_frag_read<0>(vfa, VBUF(((t) - 1) & 3)); \
;     finishSM<SH>(P0, P1, alP, l_reg, pa0, pa1, pa2, pa3); __builtin_amdgcn_s_setprio(0); SBAR(); } while (0)
; template <bool SH> __device__ __forceinline__ void attn_unit(bf16_t* __restrict__ proj, int tok0, int kv0, int seq, int h, float lam, float oscale, const float* __restrict__ subg, char* lds, bool dry) {
;     ...
;       BLK_Y1(pB0, pB1, mnB, alB, j - 2, j + 1); BLK_XK(pA0, pA1, pB0, pB1, alB, j); LANDED();
;       BLK_Y1(pA0, pA1, mnA, alA, j - 1, j + 2); BLK_XK(pB0, pB1, pA0, pA1, alA, j + 1); LANDED();
;     }
;     BLK_Y1(pB0, pB1, mnB, alB, NT - 4, NT - 1); BLK_XK(pA0, pA1, pB0, pB1, alB, NT - 2); LANDED();
	v_mfma_f32_32x32x16_bf16 v[80:95], v[80:83], v[140:143], 0
	v_add_u32_e32 v148, s27, v164
	ds_read_b128 v[144:147], v148
	ds_read_b128 v[148:151], v148 offset:8192
	v_add_u32_e32 v160, s21, v208
	v_exp_f32_e32 v96, v96
	v_exp_f32_e32 v97, v97
	v_exp_f32_e32 v98, v98
	v_exp_f32_e32 v99, v99
	v_mfma_f32_32x32x16_bf16 v[64:79], v[64:67], v[140:143], 0
	v_exp_f32_e32 v100, v100
	v_exp_f32_e32 v101, v101
	v_exp_f32_e32 v102, v102
	v_exp_f32_e32 v103, v103
	v_exp_f32_e32 v104, v104
	v_exp_f32_e32 v105, v105
	v_exp_f32_e32 v106, v106
	s_waitcnt lgkmcnt(0)
	v_mfma_f32_32x32x16_bf16 v[80:95], v[148:151], v[136:139], v[80:95]
	v_add_u32_e32 v148, s27, v163
	v_exp_f32_e32 v107, v107
	v_exp_f32_e32 v161, v109
	v_exp_f32_e32 v172, v110
	v_exp_f32_e32 v173, v111
	v_exp_f32_e32 v112, v112
	v_exp_f32_e32 v113, v113
	v_mfma_f32_32x32x16_bf16 v[64:79], v[144:147], v[136:139], v[64:79]
	ds_read_b128 v[144:147], v148
	ds_read_b128 v[148:151], v148 offset:8192
	v_exp_f32_e32 v114, v114
	v_exp_f32_e32 v115, v115
	v_exp_f32_e32 v116, v116
	v_exp_f32_e32 v117, v117
	v_exp_f32_e32 v118, v118
	v_exp_f32_e32 v119, v119
	s_waitcnt lgkmcnt(0)
	v_mfma_f32_32x32x16_bf16 v[80:95], v[148:151], v[132:135], v[80:95]
	v_add_u32_e32 v148, s27, v162
	v_exp_f32_e32 v120, v120
	v_exp_f32_e32 v121, v121
	v_exp_f32_e32 v122, v122
	v_exp_f32_e32 v123, v123
	v_exp_f32_e32 v124, v124
	v_exp_f32_e32 v125, v125
	v_mfma_f32_32x32x16_bf16 v[64:79], v[144:147], v[132:135], v[64:79]
	ds_read_b128 v[144:147], v148
	ds_read_b128 v[148:151], v148 offset:8192
	ds_read_b64_tr_b16 v[156:157], v160 offset:0
	ds_read_b64_tr_b16 v[158:159], v160 offset:0x800
	ds_read_b64_tr_b16 v[152:153], v160 offset:0x1000
	ds_read_b64_tr_b16 v[154:155], v160 offset:0x1800
	v_exp_f32_e32 v126, v126
	v_exp_f32_e32 v127, v127
	s_waitcnt lgkmcnt(0)
	v_mfma_f32_32x32x16_bf16 v[80:95], v[148:151], v[128:131], v[80:95]
	ds_read_b64_tr_b16 v[148:149], v160 offset:0x2000
	ds_read_b64_tr_b16 v[150:151], v160 offset:0x2800
	v_cvt_pk_bf16_f32 v109, v98, v99
	v_cvt_pk_bf16_f32 v110, v100, v101
	v_cvt_pk_bf16_f32 v111, v102, v103
	v_mfma_f32_32x32x16_bf16 v[64:79], v[144:147], v[128:131], v[64:79]
	ds_read_b64_tr_b16 v[144:145], v160 offset:0x3000
	ds_read_b64_tr_b16 v[146:147], v160 offset:0x3800
	v_exp_f32_e32 v160, v108
	v_add_f32_e32 v108, 0, v96
	v_add_f32_e32 v108, v97, v108
	v_add_f32_e32 v108, v98, v108
	v_add_f32_e32 v108, v99, v108
	v_add_f32_e32 v108, v100, v108
	v_add_f32_e32 v108, v101, v108
	v_add_f32_e32 v108, v102, v108
	v_add_f32_e32 v108, v103, v108
	v_add_f32_e32 v108, v104, v108
	v_add_f32_e32 v108, v105, v108
	v_add_f32_e32 v108, v106, v108
	v_add_f32_e32 v108, v107, v108
	v_add_f32_e32 v108, v160, v108
	v_add_f32_e32 v108, v161, v108
	v_add_f32_e32 v108, v172, v108
	v_add_f32_e32 v108, v173, v108
	v_add_f32_e32 v108, v112, v108
	v_add_f32_e32 v108, v113, v108
	v_add_f32_e32 v108, v114, v108
	v_add_f32_e32 v108, v115, v108
	v_add_f32_e32 v108, v116, v108
	v_add_f32_e32 v108, v117, v108
	v_add_f32_e32 v108, v118, v108
	v_add_f32_e32 v108, v119, v108
	v_add_f32_e32 v108, v120, v108
	v_add_f32_e32 v108, v121, v108
	v_add_f32_e32 v108, v122, v108
	v_add_f32_e32 v108, v123, v108
	v_add_f32_e32 v108, v124, v108
	v_add_f32_e32 v108, v125, v108
	v_add_f32_e32 v108, v126, v108
	v_add_f32_e32 v108, v127, v108
	v_add_f32_e32 v171, v171, v108
	v_cvt_pk_bf16_f32 v108, v96, v97
	v_cvt_pk_bf16_f32 v104, v104, v105
	v_cvt_pk_bf16_f32 v105, v106, v107
	v_cvt_pk_bf16_f32 v106, v160, v161
	v_cvt_pk_bf16_f32 v107, v172, v173
	v_cvt_pk_bf16_f32 v100, v112, v113
	v_cvt_pk_bf16_f32 v101, v114, v115
	v_cvt_pk_bf16_f32 v102, v116, v117
	v_cvt_pk_bf16_f32 v103, v118, v119
	v_cvt_pk_bf16_f32 v96, v120, v121
	v_cvt_pk_bf16_f32 v97, v122, v123
	v_cvt_pk_bf16_f32 v98, v124, v125
	v_cvt_pk_bf16_f32 v99, v126, v127
	s_setprio 0
	s_add_i32 s18, s18, 2
	s_waitcnt vmcnt(0)
	s_add_u32 s12, s12, 0xc0000
	s_addc_u32 s13, s13, 0
	s_cmp_ge_u32 s18, s56
	s_mov_b32 s20, s26
	s_barrier
	s_cbranch_scc0 .LBB0_355
	s_waitcnt lgkmcnt(0)
	v_or_b32_e32 v112, 0x2000, v209
	v_add_u32_e32 v173, v167, v112
	v_add_u32_e32 v172, v168, v112
	v_add_u32_e32 v168, v169, v112
	v_add_u32_e32 v167, v170, v112
	ds_read_b64_tr_b16 v[112:113], v208 offset:0x200
	ds_read_b64_tr_b16 v[114:115], v208 offset:0xa00
	ds_read_b64_tr_b16 v[116:117], v208 offset:0x1200
	ds_read_b64_tr_b16 v[118:119], v208 offset:0x1a00
	ds_read_b64_tr_b16 v[120:121], v208 offset:0x2200
	ds_read_b64_tr_b16 v[122:123], v208 offset:0x2a00
	ds_read_b64_tr_b16 v[124:125], v208 offset:0x3200
	ds_read_b64_tr_b16 v[126:127], v208 offset:0x3a00
	v_mfma_f32_32x32x16_bf16 v[48:63], v[108:111], v[156:159], v[48:63]
	s_add_i32 s12, s56, -1
	s_mul_i32 s21, s12, 0x60000
	s_mul_hi_u32 s20, s12, 0x60000
	s_add_u32 s12, s10, s21
	s_addc_u32 s13, s11, s20
	s_add_i32 s10, 0, 0x18000
	s_add_i32 s11, s17, s10
	v_mfma_f32_32x32x16_bf16 v[48:63], v[104:107], v[152:155], v[48:63]
	s_setprio 3
	s_mov_b32 s18, m0
	s_mov_b32 m0, s11
	s_nop 0
	global_load_lds_dwordx4 v166, s[12:13]
	s_mov_b32 m0, s18
	s_setprio 0
	s_add_u32 s18, s12, 0xfffe8000
	s_addc_u32 s19, s13, -1
	s_add_i32 s11, s5, 0x17000
	s_setprio 3
	s_mov_b32 s26, m0
	s_mov_b32 m0, s11
	s_nop 0
	global_load_lds_dwordx4 v166, s[18:19]
	s_mov_b32 m0, s26
	s_setprio 0
	v_mfma_f32_32x32x16_bf16 v[48:63], v[100:103], v[148:151], v[48:63]
	v_mfma_f32_32x32x16_bf16 v[48:63], v[96:99], v[144:147], v[48:63]
	s_waitcnt lgkmcnt(0)
; #define LANDED() do { asm volatile("s_waitcnt vmcnt(0)" ::: "memory"); __syncthreads(); } while (0)
; #define BLK_X(N0, N1, P0, P1, alP, t) do { SBAR(); __builtin_amdgcn_s_setprio(1); qkt(N0, N1, KBUF((t) & 3), qr, r32, hi, mapB); \
;     if constexpr (!SH) v_frag_read<0>(vfa, VBUF(((t) - 1) & 3)); \
;     finishSM<SH>(P0, P1, alP, l_reg, pa0, pa1, pa2, pa3); __builtin_amdgcn_s_setprio(0); SBAR(); } while (0)
; #define BLK_XK(N0, N1, P0, P1, alP, t) do { SBAR(); __builtin_amdgcn_s_setprio(1); \
;     if constexpr (SH) qkt(N0, N1, KBUF((t) & 3), qr, r32, hi, mapB); else qkt_k(N0, N1, KBUF((t) & 3), kf, qr, r32, hi, mapB); \
;     if constexpr (!SH) v_frag_read<0>(vfa, VBUF(((t) - 1) & 3)); \
;     finishSM<SH>(P0, P1, alP, l_reg, pa0, pa1, pa2, pa3); __builtin_amdgcn_s_setprio(0); SBAR(); } while (0)
; #define BLK_Y(C0, C1, mnC, alC, t) do { if constexpr (SH) pv_d0(o, VBUF((t) & 3), pa0, pa1, pa2, pa3); else pv_d0_pipe<true>(o, VBUF((t) & 3), pa0, pa1, pa2, pa3, vfa); partialSM<SH>(C0, C1, m_reg, mnC, alC); RESC(alC); } while (0)
; template <bool SH> __device__ __forceinline__ void attn_unit(bf16_t* __restrict__ proj, int tok0, int kv0, int seq, int h, float lam, float oscale, const float* __restrict__ subg, char* lds, bool dry) {
;     ...
;     BLK_Y1(pB0, pB1, mnB, alB, NT - 4, NT - 1); BLK_XK(pA0, pA1, pB0, pB1, alB, NT - 2); LANDED();
;     BLK_Y(pA0, pA1, mnA, alA, NT - 3); BLK_X(pB0, pB1, pA0, pA1, alA, NT - 1);
	ds_read_b64_tr_b16 v[144:145], v208 offset:0x400
	ds_read_b64_tr_b16 v[146:147], v208 offset:0xc00
	ds_read_b64_tr_b16 v[148:149], v208 offset:0x1400
	ds_read_b64_tr_b16 v[150:151], v208 offset:0x1c00
	ds_read_b64_tr_b16 v[152:153], v208 offset:0x2400
	ds_read_b64_tr_b16 v[154:155], v208 offset:0x2c00
	ds_read_b64_tr_b16 v[156:157], v208 offset:0x3400
	ds_read_b64_tr_b16 v[158:159], v208 offset:0x3c00
	v_mfma_f32_32x32x16_bf16 v[32:47], v[108:111], v[112:115], v[32:47]
	s_add_u32 s18, s12, 0x30000
	s_addc_u32 s19, s13, 0
	s_add_i32 s11, s5, 0x1a000
	s_setprio 3
	s_mov_b32 s26, m0
	s_mov_b32 m0, s11
	s_nop 0
	global_load_lds_dwordx4 v166, s[18:19]
	s_mov_b32 m0, s26
	s_setprio 0
	s_add_u32 s12, s12, 0x18000
	s_addc_u32 s13, s13, 0
	s_add_i32 s11, s5, 0x19000
	v_mfma_f32_32x32x16_bf16 v[32:47], v[104:107], v[116:119], v[32:47]
	s_setprio 3
	s_mov_b32 s18, m0
	s_mov_b32 m0, s11
	s_nop 0
	global_load_lds_dwordx4 v166, s[12:13]
	s_mov_b32 m0, s18
	s_setprio 0
	v_mfma_f32_32x32x16_bf16 v[32:47], v[100:103], v[120:123], v[32:47]
	v_mfma_f32_32x32x16_bf16 v[32:47], v[96:99], v[124:127], v[32:47]
	s_waitcnt lgkmcnt(0)
	ds_read_b64_tr_b16 v[112:113], v208 offset:0x600
	ds_read_b64_tr_b16 v[114:115], v208 offset:0xe00
	ds_read_b64_tr_b16 v[116:117], v208 offset:0x1600
	ds_read_b64_tr_b16 v[118:119], v208 offset:0x1e00
	ds_read_b64_tr_b16 v[120:121], v208 offset:0x2600
	ds_read_b64_tr_b16 v[122:123], v208 offset:0x2e00
	ds_read_b64_tr_b16 v[124:125], v208 offset:0x3600
	ds_read_b64_tr_b16 v[126:127], v208 offset:0x3e00
	v_mfma_f32_32x32x16_bf16 v[16:31], v[108:111], v[144:147], v[16:31]
	s_add_u32 s12, s8, s21
	s_addc_u32 s13, s9, s20
	s_add_i32 s8, 0, 0x1c000
	s_add_i32 s17, s17, s8
	s_setprio 3
	s_mov_b32 s9, m0
	s_mov_b32 m0, s17
	s_nop 0
	global_load_lds_dwordx4 v207, s[12:13]
	s_mov_b32 m0, s9
	s_setprio 0
	v_mfma_f32_32x32x16_bf16 v[16:31], v[104:107], v[148:151], v[16:31]
	v_mfma_f32_32x32x16_bf16 v[16:31], v[100:103], v[152:155], v[16:31]
	v_mfma_f32_32x32x16_bf16 v[16:31], v[96:99], v[156:159], v[16:31]
	s_waitcnt lgkmcnt(0)
	v_mfma_f32_32x32x16_bf16 v[0:15], v[108:111], v[112:115], v[0:15]
	s_add_u32 s12, s12, 0x30000
	s_addc_u32 s13, s13, 0
	s_add_i32 s9, s5, 0x1e000
	s_setprio 3
	s_mov_b32 s11, m0
	s_mov_b32 m0, s9
	s_nop 0
	global_load_lds_dwordx4 v207, s[12:13]
	s_mov_b32 m0, s11
	s_setprio 0
	s_add_i32 s9, 0, 0x10000
	v_mfma_f32_32x32x16_bf16 v[0:15], v[104:107], v[116:119], v[0:15]
	v_add_u32_e32 v104, s9, v173
	v_mfma_f32_32x32x16_bf16 v[0:15], v[100:103], v[120:123], v[0:15]
	v_add_u32_e32 v100, s9, v165
	ds_read_b128 v[100:103], v100
	ds_read_b128 v[112:115], v104
	v_mfma_f32_32x32x16_bf16 v[0:15], v[96:99], v[124:127], v[0:15]
	s_setprio 1
	v_add_u32_e32 v144, s9, v164
	ds_read_b128 v[144:147], v144
	s_waitcnt lgkmcnt(2)
	v_mfma_f32_32x32x16_bf16 v[96:111], v[100:103], v[140:143], 0
	v_add_u32_e32 v148, s9, v172
	ds_read_b128 v[148:151], v148
	v_exp_f32_e32 v64, v64
	v_exp_f32_e32 v65, v65
	v_exp_f32_e32 v66, v66
	v_exp_f32_e32 v67, v67
	v_exp_f32_e32 v68, v68
	s_waitcnt lgkmcnt(1)
	v_mfma_f32_32x32x16_bf16 v[96:111], v[144:147], v[136:139], v[96:111]
	v_add_u32_e32 v144, s9, v163
	ds_read_b128 v[144:147], v144
	v_exp_f32_e32 v69, v69
	v_exp_f32_e32 v70, v70
	v_exp_f32_e32 v71, v71
	v_exp_f32_e32 v72, v72
	v_exp_f32_e32 v73, v73
	v_mfma_f32_32x32x16_bf16 v[112:127], v[112:115], v[140:143], 0
	v_exp_f32_e32 v74, v74
	v_exp_f32_e32 v75, v75
	v_exp_f32_e32 v76, v76
	v_exp_f32_e32 v77, v77
	v_exp_f32_e32 v78, v78
	v_exp_f32_e32 v79, v79
	v_exp_f32_e32 v80, v80
	s_waitcnt lgkmcnt(1)
	v_mfma_f32_32x32x16_bf16 v[112:127], v[148:151], v[136:139], v[112:127]
	v_add_u32_e32 v148, s9, v168
	ds_read_b128 v[148:151], v148
	v_exp_f32_e32 v81, v81
	v_exp_f32_e32 v82, v82
	v_exp_f32_e32 v83, v83
	v_exp_f32_e32 v84, v84
	v_exp_f32_e32 v85, v85
	s_waitcnt lgkmcnt(1)
	v_mfma_f32_32x32x16_bf16 v[96:111], v[144:147], v[132:135], v[96:111]
	v_add_u32_e32 v144, s9, v162
	ds_read_b128 v[144:147], v144
	v_exp_f32_e32 v86, v86
	v_exp_f32_e32 v87, v87
	v_exp_f32_e32 v88, v88
	v_exp_f32_e32 v89, v89
	v_exp_f32_e32 v90, v90
	s_waitcnt lgkmcnt(1)
	v_mfma_f32_32x32x16_bf16 v[112:127], v[148:151], v[132:135], v[112:127]
	v_add_u32_e32 v148, s9, v167
	ds_read_b128 v[148:151], v148
	s_add_i32 s9, 0, 0xc000
	v_exp_f32_e32 v91, v91
	v_exp_f32_e32 v92, v92
	v_exp_f32_e32 v93, v93
	v_exp_f32_e32 v94, v94
	s_waitcnt lgkmcnt(1)
	v_mfma_f32_32x32x16_bf16 v[96:111], v[144:147], v[128:131], v[96:111]
	v_add_f32_e32 v144, 0, v64
	v_add_f32_e32 v144, v65, v144
	v_add_f32_e32 v144, v66, v144
	v_add_f32_e32 v144, v67, v144
	v_add_f32_e32 v144, v68, v144
	v_add_f32_e32 v144, v69, v144
	v_add_f32_e32 v144, v70, v144
	v_add_f32_e32 v144, v71, v144
	v_add_f32_e32 v144, v72, v144
	v_add_f32_e32 v144, v73, v144
	v_add_f32_e32 v144, v74, v144
	v_add_f32_e32 v144, v75, v144
	v_add_f32_e32 v144, v76, v144
	v_add_f32_e32 v144, v77, v144
	v_add_f32_e32 v144, v78, v144
	v_add_f32_e32 v144, v79, v144
	v_add_f32_e32 v144, v80, v144
	v_add_f32_e32 v144, v81, v144
	v_add_f32_e32 v144, v82, v144
	v_add_f32_e32 v144, v83, v144
	v_add_f32_e32 v144, v84, v144
	v_add_f32_e32 v144, v85, v144
	v_add_u32_e32 v145, s9, v206
	ds_read_b64_tr_b16 v[146:147], v145 offset:0
	v_add_f32_e32 v144, v86, v144
	s_waitcnt lgkmcnt(0)
	v_mfma_f32_32x32x16_bf16 v[112:127], v[148:151], v[128:131], v[112:127]
	ds_read_b64_tr_b16 v[148:149], v145 offset:0x800
	v_add_f32_e32 v144, v87, v144
	ds_read_b64_tr_b16 v[150:151], v145 offset:0x1000
	v_add_f32_e32 v144, v88, v144
	ds_read_b64_tr_b16 v[152:153], v145 offset:0x1800
	v_add_f32_e32 v144, v89, v144
	ds_read_b64_tr_b16 v[154:155], v145 offset:0x2000
	v_add_f32_e32 v144, v90, v144
	ds_read_b64_tr_b16 v[156:157], v145 offset:0x2800
	v_exp_f32_e32 v95, v95
	v_add_f32_e32 v144, v91, v144
	ds_read_b64_tr_b16 v[174:175], v145 offset:0x3000
	v_add_f32_e32 v144, v92, v144
	ds_read_b64_tr_b16 v[176:177], v145 offset:0x3800
	v_add_f32_e32 v144, v93, v144
	v_add_f32_e32 v144, v94, v144
	v_add_f32_e32 v144, v95, v144
	v_add_f32_e32 v144, v171, v144
	v_cvt_pk_bf16_f32 v64, v64, v65
	v_cvt_pk_bf16_f32 v65, v66, v67
	v_cvt_pk_bf16_f32 v66, v68, v69
	v_cvt_pk_bf16_f32 v67, v70, v71
	v_cvt_pk_bf16_f32 v68, v72, v73
	v_cvt_pk_bf16_f32 v69, v74, v75
	v_cvt_pk_bf16_f32 v70, v76, v77
	v_cvt_pk_bf16_f32 v71, v78, v79
	v_cvt_pk_bf16_f32 v72, v80, v81
	v_cvt_pk_bf16_f32 v73, v82, v83
	v_cvt_pk_bf16_f32 v74, v84, v85
	v_cvt_pk_bf16_f32 v75, v86, v87
	v_cvt_pk_bf16_f32 v76, v88, v89
	v_cvt_pk_bf16_f32 v77, v90, v91
	v_cvt_pk_bf16_f32 v78, v92, v93
	v_cvt_pk_bf16_f32 v79, v94, v95
	s_setprio 0
	s_waitcnt vmcnt(0)
	s_barrier
; #define SBAR() __builtin_amdgcn_sched_barrier(0)
; #define BLK_X(N0, N1, P0, P1, alP, t) do { SBAR(); __builtin_amdgcn_s_setprio(1); qkt(N0, N1, KBUF((t) & 3), qr, r32, hi, mapB); \
;     if constexpr (!SH) v_frag_read<0>(vfa, VBUF(((t) - 1) & 3)); \
;     finishSM<SH>(P0, P1, alP, l_reg, pa0, pa1, pa2, pa3); __builtin_amdgcn_s_setprio(0); SBAR(); } while (0)
; #define BLK_Y(C0, C1, mnC, alC, t) do { if constexpr (SH) pv_d0(o, VBUF((t) & 3), pa0, pa1, pa2, pa3); else pv_d0_pipe<true>(o, VBUF((t) & 3), pa0, pa1, pa2, pa3, vfa); partialSM<SH>(C0, C1, m_reg, mnC, alC); RESC(alC); } while (0)
; template <bool PRE> __device__ __forceinline__ void pv_d0_pipe(f32x16* o, int vb, bf16x8 pa0, bf16x8 pa1, bf16x8 pa2, bf16x8 pa3, VFrag& fa) {
;   VFrag fb;
;   if constexpr (!PRE) v_frag_read<0>(fa, vb);
;   asm volatile("s_waitcnt lgkmcnt(0)" ::: "memory"); SBAR();
;   v_frag_read<1>(fb, vb); SBAR(); v_frag_mma(o[0], fa, pa0, pa1, pa2, pa3); SBAR(); asm volatile("s_waitcnt lgkmcnt(0)" ::: "memory"); SBAR();
;   v_frag_read<2>(fa, vb); SBAR(); v_frag_mma(o[1], fb, pa0, pa1, pa2, pa3); SBAR(); asm volatile("s_waitcnt lgkmcnt(0)" ::: "memory"); SBAR();
;   v_frag_read<3>(fb, vb); SBAR(); v_frag_mma(o[2], fa, pa0, pa1, pa2, pa3); SBAR(); asm volatile("s_waitcnt lgkmcnt(0)" ::: "memory"); SBAR();
;   v_frag_mma(o[3], fb, pa0, pa1, pa2, pa3);
; }
; template <bool SH> __device__ __forceinline__ void attn_unit(bf16_t* __restrict__ proj, int tok0, int kv0, int seq, int h, float lam, float oscale, const float* __restrict__ subg, char* lds, bool dry) {
;     ...
;     BLK_Y(pA0, pA1, mnA, alA, NT - 3); BLK_X(pB0, pB1, pA0, pA1, alA, NT - 1);
	s_waitcnt lgkmcnt(0)
	ds_read_b64_tr_b16 v[80:81], v145 offset:0x200
	ds_read_b64_tr_b16 v[82:83], v145 offset:0xa00
	ds_read_b64_tr_b16 v[84:85], v145 offset:0x1200
	ds_read_b64_tr_b16 v[86:87], v145 offset:0x1a00
	ds_read_b64_tr_b16 v[88:89], v145 offset:0x2200
	ds_read_b64_tr_b16 v[90:91], v145 offset:0x2a00
	ds_read_b64_tr_b16 v[92:93], v145 offset:0x3200
	ds_read_b64_tr_b16 v[94:95], v145 offset:0x3a00
	v_mfma_f32_32x32x16_bf16 v[48:63], v[64:67], v[146:149], v[48:63]
	v_mfma_f32_32x32x16_bf16 v[48:63], v[68:71], v[150:153], v[48:63]
	v_mfma_f32_32x32x16_bf16 v[48:63], v[72:75], v[154:157], v[48:63]
	v_mfma_f32_32x32x16_bf16 v[48:63], v[76:79], v[174:177], v[48:63]
	s_waitcnt lgkmcnt(0)
	ds_read_b64_tr_b16 v[146:147], v145 offset:0x400
	ds_read_b64_tr_b16 v[148:149], v145 offset:0xc00
	ds_read_b64_tr_b16 v[150:151], v145 offset:0x1400
	ds_read_b64_tr_b16 v[152:153], v145 offset:0x1c00
	ds_read_b64_tr_b16 v[154:155], v145 offset:0x2400
	ds_read_b64_tr_b16 v[156:157], v145 offset:0x2c00
	ds_read_b64_tr_b16 v[174:175], v145 offset:0x3400
	ds_read_b64_tr_b16 v[176:177], v145 offset:0x3c00
	v_mfma_f32_32x32x16_bf16 v[32:47], v[64:67], v[80:83], v[32:47]
	v_mfma_f32_32x32x16_bf16 v[32:47], v[68:71], v[84:87], v[32:47]
	v_mfma_f32_32x32x16_bf16 v[32:47], v[72:75], v[88:91], v[32:47]
	v_mfma_f32_32x32x16_bf16 v[32:47], v[76:79], v[92:95], v[32:47]
	s_waitcnt lgkmcnt(0)
	ds_read_b64_tr_b16 v[80:81], v145 offset:0x600
	ds_read_b64_tr_b16 v[82:83], v145 offset:0xe00
	ds_read_b64_tr_b16 v[84:85], v145 offset:0x1600
	ds_read_b64_tr_b16 v[86:87], v145 offset:0x1e00
	ds_read_b64_tr_b16 v[88:89], v145 offset:0x2600
	ds_read_b64_tr_b16 v[90:91], v145 offset:0x2e00
	ds_read_b64_tr_b16 v[92:93], v145 offset:0x3600
	ds_read_b64_tr_b16 v[94:95], v145 offset:0x3e00
	v_mfma_f32_32x32x16_bf16 v[16:31], v[64:67], v[146:149], v[16:31]
	v_mfma_f32_32x32x16_bf16 v[16:31], v[68:71], v[150:153], v[16:31]
	v_mfma_f32_32x32x16_bf16 v[16:31], v[72:75], v[154:157], v[16:31]
	v_mfma_f32_32x32x16_bf16 v[16:31], v[76:79], v[174:177], v[16:31]
	s_waitcnt lgkmcnt(0)
	v_mfma_f32_32x32x16_bf16 v[0:15], v[64:67], v[80:83], v[0:15]
	v_mfma_f32_32x32x16_bf16 v[0:15], v[68:71], v[84:87], v[0:15]
	v_mfma_f32_32x32x16_bf16 v[0:15], v[72:75], v[88:91], v[0:15]
	v_mfma_f32_32x32x16_bf16 v[0:15], v[76:79], v[92:95], v[0:15]
	s_setprio 1
	v_add_u32_e32 v64, s10, v165
	ds_read_b128 v[64:67], v64
	v_add_u32_e32 v68, s10, v173
	ds_read_b128 v[80:83], v68
	v_add_u32_e32 v145, s10, v164
	ds_read_b128 v[146:149], v145
	v_add_u32_e32 v145, s10, v172
	ds_read_b128 v[150:153], v145
	v_add_u32_e32 v145, s10, v163
	s_add_i32 s9, 0, 0x14000
	s_waitcnt lgkmcnt(3)
	v_mfma_f32_32x32x16_bf16 v[64:79], v[64:67], v[140:143], 0
	v_exp_f32_e32 v154, v100
	v_exp_f32_e32 v100, v116
	v_exp_f32_e32 v156, v101
	v_exp_f32_e32 v158, v102
	v_exp_f32_e32 v102, v118
	v_exp_f32_e32 v116, v119
	v_exp_f32_e32 v118, v120
	s_waitcnt lgkmcnt(2)
	v_mfma_f32_32x32x16_bf16 v[80:95], v[80:83], v[140:143], 0
	v_exp_f32_e32 v164, v105
	v_exp_f32_e32 v166, v106
	v_exp_f32_e32 v106, v122
	v_exp_f32_e32 v170, v107
	v_exp_f32_e32 v120, v123
	v_exp_f32_e32 v172, v108
	v_exp_f32_e32 v108, v124
	s_waitcnt lgkmcnt(1)
	v_mfma_f32_32x32x16_bf16 v[64:79], v[146:149], v[136:139], v[64:79]
	ds_read_b128 v[146:149], v145
	v_add_u32_e32 v145, s10, v168
	v_exp_f32_e32 v168, v104
	v_exp_f32_e32 v104, v121
	v_exp_f32_e32 v174, v109
	v_exp_f32_e32 v122, v125
	v_exp_f32_e32 v176, v110
	s_waitcnt lgkmcnt(1)
	v_mfma_f32_32x32x16_bf16 v[80:95], v[150:153], v[136:139], v[80:95]
	ds_read_b128 v[150:153], v145
	v_add_u32_e32 v145, s10, v162
	v_exp_f32_e32 v162, v103
	v_exp_f32_e32 v110, v126
	v_exp_f32_e32 v126, v111
	v_exp_f32_e32 v124, v127
	v_cvt_pk_bf16_f32 v226, v154, v156
	s_waitcnt lgkmcnt(1)
	v_mfma_f32_32x32x16_bf16 v[64:79], v[146:149], v[132:135], v[64:79]
	ds_read_b128 v[146:149], v145
	v_add_u32_e32 v145, s10, v167
	v_cvt_pk_bf16_f32 v227, v158, v162
	v_cvt_pk_bf16_f32 v228, v168, v164
	v_cvt_pk_bf16_f32 v229, v166, v170
	v_cvt_pk_bf16_f32 v230, v172, v174
	v_cvt_pk_bf16_f32 v231, v176, v126
	s_waitcnt lgkmcnt(1)
	v_mfma_f32_32x32x16_bf16 v[80:95], v[150:153], v[132:135], v[80:95]
	ds_read_b128 v[150:153], v145
	v_add_u32_e32 v145, s9, v206
	ds_read_b64_tr_b16 v[194:195], v145 offset:0
	ds_read_b64_tr_b16 v[196:197], v145 offset:0x800
	ds_read_b64_tr_b16 v[212:213], v145 offset:0x1000
	ds_read_b64_tr_b16 v[214:215], v145 offset:0x1800
	ds_read_b64_tr_b16 v[216:217], v145 offset:0x2000
	s_waitcnt lgkmcnt(0)
	v_mfma_f32_32x32x16_bf16 v[80:95], v[150:153], v[128:131], v[80:95]
	ds_read_b64_tr_b16 v[218:219], v145 offset:0x2800
	ds_read_b64_tr_b16 v[220:221], v145 offset:0x3000
	v_exp_f32_e32 v150, v98
	v_exp_f32_e32 v98, v114
	v_exp_f32_e32 v152, v99
	v_exp_f32_e32 v114, v117
	ds_read_b64_tr_b16 v[222:223], v145 offset:0x3800
	v_mfma_f32_32x32x16_bf16 v[64:79], v[146:149], v[128:131], v[64:79]
	v_exp_f32_e32 v147, v96
	v_exp_f32_e32 v146, v112
	v_exp_f32_e32 v148, v97
	v_exp_f32_e32 v96, v113
	v_exp_f32_e32 v112, v115
	v_add_f32_e32 v160, 0, v147
	v_cvt_pk_bf16_f32 v224, v147, v148
	v_cvt_pk_bf16_f32 v225, v150, v152
	v_cvt_pk_bf16_f32 v232, v146, v96
	v_cvt_pk_bf16_f32 v233, v98, v112
	v_cvt_pk_bf16_f32 v234, v100, v114
	v_cvt_pk_bf16_f32 v235, v102, v116
	v_cvt_pk_bf16_f32 v236, v118, v104
	v_cvt_pk_bf16_f32 v237, v106, v120
	v_cvt_pk_bf16_f32 v238, v108, v122
	v_cvt_pk_bf16_f32 v239, v110, v124
	s_setprio 0
	s_waitcnt lgkmcnt(0)
; #define SBAR() __builtin_amdgcn_sched_barrier(0)
; #define BLK_Y(C0, C1, mnC, alC, t) do { if constexpr (SH) pv_d0(o, VBUF((t) & 3), pa0, pa1, pa2, pa3); else pv_d0_pipe<true>(o, VBUF((t) & 3), pa0, pa1, pa2, pa3, vfa); partialSM<SH>(C0, C1, m_reg, mnC, alC); RESC(alC); } while (0)
; template <bool SH> __device__ __forceinline__ void attn_unit(bf16_t* __restrict__ proj, int tok0, int kv0, int seq, int h, float lam, float oscale, const float* __restrict__ subg, char* lds, bool dry) {
;     ...
;     BLK_Y(pB0, pB1, mnB, alB, NT - 2);
;     finishSM<SH>(pB0, pB1, alB, l_reg, pa0, pa1, pa2, pa3); SBAR();
;     if constexpr (SH) pv_d0(o, VBUF((NT - 1) & 3), pa0, pa1, pa2, pa3); else pv_d0_pipe<false>(o, VBUF((NT - 1) & 3), pa0, pa1, pa2, pa3, vfa);
	ds_read_b64_tr_b16 v[240:241], v145 offset:0x200
	ds_read_b64_tr_b16 v[242:243], v145 offset:0xa00
	ds_read_b64_tr_b16 v[244:245], v145 offset:0x1200
	ds_read_b64_tr_b16 v[246:247], v145 offset:0x1a00
	ds_read_b64_tr_b16 v[248:249], v145 offset:0x2200
	ds_read_b64_tr_b16 v[250:251], v145 offset:0x2a00
	ds_read_b64_tr_b16 v[186:187], v145 offset:0x3200
	ds_read_b64_tr_b16 v[188:189], v145 offset:0x3a00
	v_mfma_f32_32x32x16_bf16 v[48:63], v[224:227], v[194:197], v[48:63]
	v_mfma_f32_32x32x16_bf16 v[48:63], v[228:231], v[212:215], v[48:63]
	v_mfma_f32_32x32x16_bf16 v[48:63], v[232:235], v[216:219], v[48:63]
	v_mfma_f32_32x32x16_bf16 v[48:63], v[236:239], v[220:223], v[48:63]
	s_waitcnt lgkmcnt(0)
	ds_read_b64_tr_b16 v[194:195], v145 offset:0x400
	ds_read_b64_tr_b16 v[196:197], v145 offset:0xc00
	ds_read_b64_tr_b16 v[212:213], v145 offset:0x1400
	ds_read_b64_tr_b16 v[214:215], v145 offset:0x1c00
	ds_read_b64_tr_b16 v[216:217], v145 offset:0x2400
	ds_read_b64_tr_b16 v[218:219], v145 offset:0x2c00
	ds_read_b64_tr_b16 v[220:221], v145 offset:0x3400
	ds_read_b64_tr_b16 v[222:223], v145 offset:0x3c00
	v_mfma_f32_32x32x16_bf16 v[32:47], v[224:227], v[240:243], v[32:47]
	v_mfma_f32_32x32x16_bf16 v[32:47], v[228:231], v[244:247], v[32:47]
	v_mfma_f32_32x32x16_bf16 v[32:47], v[232:235], v[248:251], v[32:47]
	v_mfma_f32_32x32x16_bf16 v[32:47], v[236:239], v[186:189], v[32:47]
	s_waitcnt lgkmcnt(0)
	ds_read_b64_tr_b16 v[186:187], v145 offset:0x600
	ds_read_b64_tr_b16 v[188:189], v145 offset:0xe00
	ds_read_b64_tr_b16 v[240:241], v145 offset:0x1600
	ds_read_b64_tr_b16 v[242:243], v145 offset:0x1e00
	ds_read_b64_tr_b16 v[244:245], v145 offset:0x2600
	ds_read_b64_tr_b16 v[246:247], v145 offset:0x2e00
	ds_read_b64_tr_b16 v[248:249], v145 offset:0x3600
	ds_read_b64_tr_b16 v[250:251], v145 offset:0x3e00
	v_mfma_f32_32x32x16_bf16 v[16:31], v[224:227], v[194:197], v[16:31]
	v_mfma_f32_32x32x16_bf16 v[16:31], v[228:231], v[212:215], v[16:31]
	v_mfma_f32_32x32x16_bf16 v[16:31], v[232:235], v[216:219], v[16:31]
	v_mfma_f32_32x32x16_bf16 v[16:31], v[236:239], v[220:223], v[16:31]
	s_waitcnt lgkmcnt(0)
	v_exp_f32_e32 v149, v64
	v_exp_f32_e32 v151, v65
	v_exp_f32_e32 v153, v66
	v_exp_f32_e32 v155, v67
	v_mov_b32_e32 v161, v253
	v_exp_f32_e32 v157, v68
	v_pk_add_f32 v[64:65], v[148:149], v[160:161]
	v_mfma_f32_32x32x16_bf16 v[0:15], v[224:227], v[186:189], v[0:15]
	v_exp_f32_e32 v159, v69
	v_pk_add_f32 v[64:65], v[150:151], v[64:65]
	v_exp_f32_e32 v163, v70
	v_pk_add_f32 v[64:65], v[152:153], v[64:65]
	v_exp_f32_e32 v169, v71
	v_pk_add_f32 v[64:65], v[154:155], v[64:65]
	v_exp_f32_e32 v165, v72
	v_pk_add_f32 v[64:65], v[156:157], v[64:65]
	v_exp_f32_e32 v167, v73
	v_pk_add_f32 v[64:65], v[158:159], v[64:65]
	v_exp_f32_e32 v171, v74
	v_pk_add_f32 v[64:65], v[162:163], v[64:65]
	v_exp_f32_e32 v173, v75
	v_pk_add_f32 v[64:65], v[168:169], v[64:65]
	v_exp_f32_e32 v175, v76
	v_pk_add_f32 v[64:65], v[164:165], v[64:65]
	v_mfma_f32_32x32x16_bf16 v[0:15], v[228:231], v[240:243], v[0:15]
	v_exp_f32_e32 v177, v77
	v_pk_add_f32 v[64:65], v[166:167], v[64:65]
	v_exp_f32_e32 v127, v78
	v_pk_add_f32 v[64:65], v[170:171], v[64:65]
	v_exp_f32_e32 v147, v79
	v_pk_add_f32 v[64:65], v[172:173], v[64:65]
	v_exp_f32_e32 v97, v80
	v_pk_add_f32 v[64:65], v[174:175], v[64:65]
	v_exp_f32_e32 v99, v81
	v_pk_add_f32 v[64:65], v[176:177], v[64:65]
	v_exp_f32_e32 v113, v82
	v_pk_add_f32 v[64:65], v[126:127], v[64:65]
	v_exp_f32_e32 v101, v83
	v_pk_add_f32 v[64:65], v[146:147], v[64:65]
	v_exp_f32_e32 v115, v84
	v_pk_add_f32 v[64:65], v[96:97], v[64:65]
	v_mfma_f32_32x32x16_bf16 v[0:15], v[232:235], v[244:247], v[0:15]
	v_exp_f32_e32 v103, v85
	v_pk_add_f32 v[64:65], v[98:99], v[64:65]
	v_exp_f32_e32 v117, v86
	v_pk_add_f32 v[64:65], v[112:113], v[64:65]
	v_exp_f32_e32 v119, v87
	v_pk_add_f32 v[64:65], v[100:101], v[64:65]
	v_exp_f32_e32 v105, v88
	v_pk_add_f32 v[64:65], v[114:115], v[64:65]
	v_exp_f32_e32 v107, v89
	v_pk_add_f32 v[64:65], v[102:103], v[64:65]
	v_exp_f32_e32 v121, v90
	v_pk_add_f32 v[64:65], v[116:117], v[64:65]
	v_exp_f32_e32 v109, v91
	v_pk_add_f32 v[64:65], v[118:119], v[64:65]
	v_exp_f32_e32 v123, v92
	v_pk_add_f32 v[64:65], v[104:105], v[64:65]
	v_mfma_f32_32x32x16_bf16 v[0:15], v[236:239], v[248:251], v[0:15]
	v_exp_f32_e32 v111, v93
	v_pk_add_f32 v[64:65], v[106:107], v[64:65]
	v_exp_f32_e32 v125, v94
	v_pk_add_f32 v[64:65], v[120:121], v[64:65]
	v_exp_f32_e32 v145, v95
	v_pk_add_f32 v[64:65], v[108:109], v[64:65]
	v_cvt_pk_bf16_f32 v66, v157, v159
	v_pk_add_f32 v[64:65], v[122:123], v[64:65]
	v_cvt_pk_bf16_f32 v67, v163, v169
	v_pk_add_f32 v[64:65], v[110:111], v[64:65]
	v_cvt_pk_bf16_f32 v68, v165, v167
	v_pk_add_f32 v[64:65], v[124:125], v[64:65]
	v_cvt_pk_bf16_f32 v69, v171, v173
	v_pk_add_f32 v[64:65], v[144:145], v[64:65]
	v_cvt_pk_bf16_f32 v70, v175, v177
	v_add_f32_e32 v82, v64, v65
	v_cvt_pk_bf16_f32 v64, v149, v151
	v_cvt_pk_bf16_f32 v65, v153, v155
	v_cvt_pk_bf16_f32 v71, v127, v147
	v_cvt_pk_bf16_f32 v72, v97, v99
	v_cvt_pk_bf16_f32 v73, v113, v101
	v_cvt_pk_bf16_f32 v74, v115, v103
	v_cvt_pk_bf16_f32 v75, v117, v119
	v_cvt_pk_bf16_f32 v76, v105, v107
	v_cvt_pk_bf16_f32 v77, v121, v109
	v_cvt_pk_bf16_f32 v78, v123, v111
	v_cvt_pk_bf16_f32 v79, v125, v145
	v_add_u32_e32 v80, s8, v206
	ds_read_b64_tr_b16 v[84:85], v80 offset:0
	ds_read_b64_tr_b16 v[86:87], v80 offset:0x800
	ds_read_b64_tr_b16 v[88:89], v80 offset:0x1000
	ds_read_b64_tr_b16 v[90:91], v80 offset:0x1800
	ds_read_b64_tr_b16 v[92:93], v80 offset:0x2000
	ds_read_b64_tr_b16 v[94:95], v80 offset:0x2800
	ds_read_b64_tr_b16 v[96:97], v80 offset:0x3000
	ds_read_b64_tr_b16 v[98:99], v80 offset:0x3800
	s_waitcnt lgkmcnt(0)
; #define SBAR() __builtin_amdgcn_sched_barrier(0)
; template <bool PRE> __device__ __forceinline__ void pv_d0_pipe(f32x16* o, int vb, bf16x8 pa0, bf16x8 pa1, bf16x8 pa2, bf16x8 pa3, VFrag& fa) {
;   VFrag fb;
;   if constexpr (!PRE) v_frag_read<0>(fa, vb);
;   asm volatile("s_waitcnt lgkmcnt(0)" ::: "memory"); SBAR();
;   v_frag_read<1>(fb, vb); SBAR(); v_frag_mma(o[0], fa, pa0, pa1, pa2, pa3); SBAR(); asm volatile("s_waitcnt lgkmcnt(0)" ::: "memory"); SBAR();
;   v_frag_read<2>(fa, vb); SBAR(); v_frag_mma(o[1], fb, pa0, pa1, pa2, pa3); SBAR(); asm volatile("s_waitcnt lgkmcnt(0)" ::: "memory"); SBAR();
;   v_frag_read<3>(fb, vb); SBAR(); v_frag_mma(o[2], fa, pa0, pa1, pa2, pa3); SBAR(); asm volatile("s_waitcnt lgkmcnt(0)" ::: "memory"); SBAR();
;   v_frag_mma(o[3], fb, pa0, pa1, pa2, pa3);
; }
; template <bool SH> __device__ __forceinline__ void attn_unit(bf16_t* __restrict__ proj, int tok0, int kv0, int seq, int h, float lam, float oscale, const float* __restrict__ subg, char* lds, bool dry) {
;     ...
;     if constexpr (SH) pv_d0(o, VBUF((NT - 1) & 3), pa0, pa1, pa2, pa3); else pv_d0_pipe<false>(o, VBUF((NT - 1) & 3), pa0, pa1, pa2, pa3, vfa);
	ds_read_b64_tr_b16 v[100:101], v80 offset:0x200
	ds_read_b64_tr_b16 v[102:103], v80 offset:0xa00
	ds_read_b64_tr_b16 v[104:105], v80 offset:0x1200
	ds_read_b64_tr_b16 v[106:107], v80 offset:0x1a00
	ds_read_b64_tr_b16 v[108:109], v80 offset:0x2200
	ds_read_b64_tr_b16 v[110:111], v80 offset:0x2a00
	ds_read_b64_tr_b16 v[112:113], v80 offset:0x3200
	ds_read_b64_tr_b16 v[114:115], v80 offset:0x3a00
	s_nop 0
	v_mfma_f32_32x32x16_bf16 v[48:63], v[64:67], v[84:87], v[48:63]
	v_mfma_f32_32x32x16_bf16 v[48:63], v[68:71], v[88:91], v[48:63]
	v_mfma_f32_32x32x16_bf16 v[48:63], v[72:75], v[92:95], v[48:63]
	v_mfma_f32_32x32x16_bf16 v[48:63], v[76:79], v[96:99], v[48:63]
	s_waitcnt lgkmcnt(0)
	ds_read_b64_tr_b16 v[84:85], v80 offset:0x400
	ds_read_b64_tr_b16 v[86:87], v80 offset:0xc00
	ds_read_b64_tr_b16 v[88:89], v80 offset:0x1400
	ds_read_b64_tr_b16 v[90:91], v80 offset:0x1c00
	ds_read_b64_tr_b16 v[92:93], v80 offset:0x2400
	ds_read_b64_tr_b16 v[94:95], v80 offset:0x2c00
	ds_read_b64_tr_b16 v[96:97], v80 offset:0x3400
	ds_read_b64_tr_b16 v[98:99], v80 offset:0x3c00
	v_mfma_f32_32x32x16_bf16 v[32:47], v[64:67], v[100:103], v[32:47]
	v_mfma_f32_32x32x16_bf16 v[32:47], v[68:71], v[104:107], v[32:47]
	v_mfma_f32_32x32x16_bf16 v[32:47], v[72:75], v[108:111], v[32:47]
	v_mfma_f32_32x32x16_bf16 v[32:47], v[76:79], v[112:115], v[32:47]
	s_waitcnt lgkmcnt(0)
	ds_read_b64_tr_b16 v[100:101], v80 offset:0x600
	ds_read_b64_tr_b16 v[102:103], v80 offset:0xe00
	ds_read_b64_tr_b16 v[104:105], v80 offset:0x1600
	ds_read_b64_tr_b16 v[106:107], v80 offset:0x1e00
	ds_read_b64_tr_b16 v[108:109], v80 offset:0x2600
	ds_read_b64_tr_b16 v[110:111], v80 offset:0x2e00
	ds_read_b64_tr_b16 v[112:113], v80 offset:0x3600
	ds_read_b64_tr_b16 v[114:115], v80 offset:0x3e00
	v_mfma_f32_32x32x16_bf16 v[16:31], v[64:67], v[84:87], v[16:31]
	v_mfma_f32_32x32x16_bf16 v[16:31], v[68:71], v[88:91], v[16:31]
	v_mfma_f32_32x32x16_bf16 v[16:31], v[72:75], v[92:95], v[16:31]
	v_mfma_f32_32x32x16_bf16 v[16:31], v[76:79], v[96:99], v[16:31]
	s_waitcnt lgkmcnt(0)
	v_mfma_f32_32x32x16_bf16 v[0:15], v[64:67], v[100:103], v[0:15]
	s_mov_b64 s[12:13], 0
	v_mfma_f32_32x32x16_bf16 v[0:15], v[68:71], v[104:107], v[0:15]
	v_mfma_f32_32x32x16_bf16 v[0:15], v[72:75], v[108:111], v[0:15]
	v_mfma_f32_32x32x16_bf16 v[0:15], v[76:79], v[112:115], v[0:15]
